# hand-written EpiOut epilogue in P5: column constants once per tile, x quads two row groups ahead behind counted waits, stores never waited for, the eight row atomics together at the end
# speedup vs baseline: 1.0098x; 1.0043x over previous
.LBB0_764:
	v_lshl_add_u32 v147, s30, 8, v150
	v_lshl_or_b32 v145, s28, 8, v152
	s_ashr_i32 s13, s30, 3
	s_mul_hi_i32 s23, s13, 0xc000
	s_mul_i32 s13, s13, 0xc000
	s_add_u32 s13, s64, s13
	s_addc_u32 s23, s65, s23
	s_add_u32 s30, s13, 0x4000
	s_addc_u32 s31, s23, 0
	s_add_u32 s28, s13, 0x8000
	s_addc_u32 s29, s23, 0
	v_readlane_b32 s52, v253, 24
	v_readlane_b32 s53, v253, 25
	v_readlane_b32 s66, v253, 38
	v_readlane_b32 s67, v253, 39
	v_lshlrev_b32_e32 v145, 2, v145
	v_lshl_add_u32 v146, v147, 13, v145
	v_lshlrev_b32_e32 v147, 2, v147
	v_xor_b32_e32 v196, 16, v156
	v_xor_b32_e32 v197, 32, v156
	v_lshlrev_b32_e32 v196, 2, v196
	v_lshlrev_b32_e32 v197, 2, v197
	global_load_dwordx4 v[158:161], v145, s[30:31] offset:0
	global_load_dwordx4 v[162:165], v145, s[30:31] offset:16
	global_load_dwordx4 v[166:169], v145, s[30:31] offset:512
	global_load_dwordx4 v[170:173], v145, s[30:31] offset:528
	v_mov_b32_e32 v144, v146
	global_load_dwordx4 v[220:223], v144, s[52:53] offset:0
	global_load_dwordx4 v[224:227], v144, s[52:53] offset:16
	global_load_dwordx4 v[228:231], v144, s[52:53] offset:512
	global_load_dwordx4 v[232:235], v144, s[52:53] offset:528
	v_add_u32_e32 v144, 0x20000, v146
	global_load_dwordx4 v[236:239], v144, s[52:53] offset:0
	global_load_dwordx4 v[240:243], v144, s[52:53] offset:16
	global_load_dwordx4 v[244:247], v144, s[52:53] offset:512
	global_load_dwordx4 v[248:251], v144, s[52:53] offset:528
	global_load_dwordx4 v[174:177], v145, s[28:29] offset:0
	global_load_dwordx4 v[178:181], v145, s[28:29] offset:16
	global_load_dwordx4 v[182:185], v145, s[28:29] offset:512
	global_load_dwordx4 v[186:189], v145, s[28:29] offset:528
	global_load_dwordx4 v[204:207], v145, s[66:67] offset:0
	global_load_dwordx4 v[208:211], v145, s[66:67] offset:16
	global_load_dwordx4 v[212:215], v145, s[66:67] offset:512
	global_load_dwordx4 v[216:219], v145, s[66:67] offset:528
	s_waitcnt vmcnt(0)
	v_pk_add_f32 v[174:175], v[174:175], 1.0 op_sel_hi:[1,0]
	v_pk_add_f32 v[176:177], v[176:177], 1.0 op_sel_hi:[1,0]
	v_pk_mul_f32 v[174:175], v[204:205], v[174:175]
	v_pk_mul_f32 v[176:177], v[206:207], v[176:177]
	v_pk_add_f32 v[178:179], v[178:179], 1.0 op_sel_hi:[1,0]
	v_pk_add_f32 v[180:181], v[180:181], 1.0 op_sel_hi:[1,0]
	v_pk_mul_f32 v[178:179], v[208:209], v[178:179]
	v_pk_mul_f32 v[180:181], v[210:211], v[180:181]
	v_pk_add_f32 v[182:183], v[182:183], 1.0 op_sel_hi:[1,0]
	v_pk_add_f32 v[184:185], v[184:185], 1.0 op_sel_hi:[1,0]
	v_pk_mul_f32 v[182:183], v[212:213], v[182:183]
	v_pk_mul_f32 v[184:185], v[214:215], v[184:185]
	v_pk_add_f32 v[186:187], v[186:187], 1.0 op_sel_hi:[1,0]
	v_pk_add_f32 v[188:189], v[188:189], 1.0 op_sel_hi:[1,0]
	v_pk_mul_f32 v[186:187], v[216:217], v[186:187]
	v_pk_mul_f32 v[188:189], v[218:219], v[188:189]
	s_waitcnt vmcnt(12)
	v_pk_fma_f32 v[124:125], v[124:125], v[158:159], v[220:221]
	v_pk_fma_f32 v[126:127], v[126:127], v[160:161], v[222:223]
	v_pk_fma_f32 v[120:121], v[120:121], v[162:163], v[224:225]
	v_pk_fma_f32 v[122:123], v[122:123], v[164:165], v[226:227]
	v_pk_fma_f32 v[116:117], v[116:117], v[166:167], v[228:229]
	v_pk_fma_f32 v[118:119], v[118:119], v[168:169], v[230:231]
	v_pk_fma_f32 v[112:113], v[112:113], v[170:171], v[232:233]
	v_pk_fma_f32 v[114:115], v[114:115], v[172:173], v[234:235]
	v_mov_b32_e32 v194, v146
	v_lshrrev_b32_e32 v198, 1, v194
	v_add_u32_e32 v144, 0x40000, v146
	global_load_dwordx4 v[220:223], v144, s[52:53] offset:0
	global_load_dwordx4 v[224:227], v144, s[52:53] offset:16
	global_load_dwordx4 v[228:231], v144, s[52:53] offset:512
	global_load_dwordx4 v[232:235], v144, s[52:53] offset:528
	global_store_dwordx4 v194, v[124:127], s[14:15] offset:0
	global_store_dwordx4 v194, v[120:123], s[14:15] offset:16
	global_store_dwordx4 v194, v[116:119], s[14:15] offset:512
	global_store_dwordx4 v194, v[112:115], s[14:15] offset:528
	v_pk_mul_f32 v[204:205], v[124:125], v[174:175]
	v_pk_mul_f32 v[206:207], v[126:127], v[176:177]
	v_cvt_pk_bf16_f32 v200, v204, v205
	v_cvt_pk_bf16_f32 v201, v206, v207
	v_pk_mul_f32 v[204:205], v[120:121], v[178:179]
	v_pk_mul_f32 v[206:207], v[122:123], v[180:181]
	v_cvt_pk_bf16_f32 v202, v204, v205
	v_cvt_pk_bf16_f32 v203, v206, v207
	global_store_dwordx4 v198, v[200:203], s[20:21]
	v_pk_mul_f32 v[204:205], v[116:117], v[182:183]
	v_pk_mul_f32 v[206:207], v[118:119], v[184:185]
	v_cvt_pk_bf16_f32 v208, v204, v205
	v_cvt_pk_bf16_f32 v209, v206, v207
	v_pk_mul_f32 v[204:205], v[112:113], v[186:187]
	v_pk_mul_f32 v[206:207], v[114:115], v[188:189]
	v_cvt_pk_bf16_f32 v210, v204, v205
	v_cvt_pk_bf16_f32 v211, v206, v207
	global_store_dwordx4 v198, v[208:211], s[20:21] offset:256
	v_mul_f32_e32 v190, v125, v125
	v_mul_f32_e32 v195, v127, v127
	v_fmac_f32_e32 v190, v124, v124
	v_fmac_f32_e32 v195, v126, v126
	v_add_f32_e32 v190, v190, v195
	v_mul_f32_e32 v191, v121, v121
	v_mul_f32_e32 v195, v123, v123
	v_fmac_f32_e32 v191, v120, v120
	v_fmac_f32_e32 v195, v122, v122
	v_add_f32_e32 v191, v191, v195
	v_mul_f32_e32 v192, v117, v117
	v_mul_f32_e32 v195, v119, v119
	v_fmac_f32_e32 v192, v116, v116
	v_fmac_f32_e32 v195, v118, v118
	v_add_f32_e32 v192, v192, v195
	v_mul_f32_e32 v193, v113, v113
	v_mul_f32_e32 v195, v115, v115
	v_fmac_f32_e32 v193, v112, v112
	v_fmac_f32_e32 v195, v114, v114
	v_add_f32_e32 v193, v193, v195
	v_add_f32_e32 v190, v190, v191
	v_add_f32_e32 v190, v190, v192
	v_add_f32_e32 v190, v190, v193
	ds_bpermute_b32 v195, v196, v190
	s_waitcnt lgkmcnt(0)
	v_add_f32_e32 v190, v190, v195
	ds_bpermute_b32 v195, v197, v190
	s_waitcnt lgkmcnt(0)
	v_add_f32_e32 v212, v190, v195
	s_waitcnt vmcnt(18)
	v_pk_fma_f32 v[108:109], v[108:109], v[158:159], v[236:237]
	v_pk_fma_f32 v[110:111], v[110:111], v[160:161], v[238:239]
	v_pk_fma_f32 v[104:105], v[104:105], v[162:163], v[240:241]
	v_pk_fma_f32 v[106:107], v[106:107], v[164:165], v[242:243]
	v_pk_fma_f32 v[100:101], v[100:101], v[166:167], v[244:245]
	v_pk_fma_f32 v[102:103], v[102:103], v[168:169], v[246:247]
	v_pk_fma_f32 v[96:97], v[96:97], v[170:171], v[248:249]
	v_pk_fma_f32 v[98:99], v[98:99], v[172:173], v[250:251]
	v_add_u32_e32 v194, 0x20000, v146
	v_lshrrev_b32_e32 v198, 1, v194
	v_add_u32_e32 v144, 0x60000, v146
	global_load_dwordx4 v[236:239], v144, s[52:53] offset:0
	global_load_dwordx4 v[240:243], v144, s[52:53] offset:16
	global_load_dwordx4 v[244:247], v144, s[52:53] offset:512
	global_load_dwordx4 v[248:251], v144, s[52:53] offset:528
	global_store_dwordx4 v194, v[108:111], s[14:15] offset:0
	global_store_dwordx4 v194, v[104:107], s[14:15] offset:16
	global_store_dwordx4 v194, v[100:103], s[14:15] offset:512
	global_store_dwordx4 v194, v[96:99], s[14:15] offset:528
	v_pk_mul_f32 v[204:205], v[108:109], v[174:175]
	v_pk_mul_f32 v[206:207], v[110:111], v[176:177]
	v_cvt_pk_bf16_f32 v200, v204, v205
	v_cvt_pk_bf16_f32 v201, v206, v207
	v_pk_mul_f32 v[204:205], v[104:105], v[178:179]
	v_pk_mul_f32 v[206:207], v[106:107], v[180:181]
	v_cvt_pk_bf16_f32 v202, v204, v205
	v_cvt_pk_bf16_f32 v203, v206, v207
	global_store_dwordx4 v198, v[200:203], s[20:21]
	v_pk_mul_f32 v[204:205], v[100:101], v[182:183]
	v_pk_mul_f32 v[206:207], v[102:103], v[184:185]
	v_cvt_pk_bf16_f32 v208, v204, v205
	v_cvt_pk_bf16_f32 v209, v206, v207
	v_pk_mul_f32 v[204:205], v[96:97], v[186:187]
	v_pk_mul_f32 v[206:207], v[98:99], v[188:189]
	v_cvt_pk_bf16_f32 v210, v204, v205
	v_cvt_pk_bf16_f32 v211, v206, v207
	global_store_dwordx4 v198, v[208:211], s[20:21] offset:256
	v_mul_f32_e32 v190, v109, v109
	v_mul_f32_e32 v195, v111, v111
	v_fmac_f32_e32 v190, v108, v108
	v_fmac_f32_e32 v195, v110, v110
	v_add_f32_e32 v190, v190, v195
	v_mul_f32_e32 v191, v105, v105
	v_mul_f32_e32 v195, v107, v107
	v_fmac_f32_e32 v191, v104, v104
	v_fmac_f32_e32 v195, v106, v106
	v_add_f32_e32 v191, v191, v195
	v_mul_f32_e32 v192, v101, v101
	v_mul_f32_e32 v195, v103, v103
	v_fmac_f32_e32 v192, v100, v100
	v_fmac_f32_e32 v195, v102, v102
	v_add_f32_e32 v192, v192, v195
	v_mul_f32_e32 v193, v97, v97
	v_mul_f32_e32 v195, v99, v99
	v_fmac_f32_e32 v193, v96, v96
	v_fmac_f32_e32 v195, v98, v98
	v_add_f32_e32 v193, v193, v195
	v_add_f32_e32 v190, v190, v191
	v_add_f32_e32 v190, v190, v192
	v_add_f32_e32 v190, v190, v193
	ds_bpermute_b32 v195, v196, v190
	s_waitcnt lgkmcnt(0)
	v_add_f32_e32 v190, v190, v195
	ds_bpermute_b32 v195, v197, v190
	s_waitcnt lgkmcnt(0)
	v_add_f32_e32 v213, v190, v195
	s_waitcnt vmcnt(16)
	v_pk_fma_f32 v[92:93], v[92:93], v[158:159], v[220:221]
	v_pk_fma_f32 v[94:95], v[94:95], v[160:161], v[222:223]
	v_pk_fma_f32 v[88:89], v[88:89], v[162:163], v[224:225]
	v_pk_fma_f32 v[90:91], v[90:91], v[164:165], v[226:227]
	v_pk_fma_f32 v[84:85], v[84:85], v[166:167], v[228:229]
	v_pk_fma_f32 v[86:87], v[86:87], v[168:169], v[230:231]
	v_pk_fma_f32 v[80:81], v[80:81], v[170:171], v[232:233]
	v_pk_fma_f32 v[82:83], v[82:83], v[172:173], v[234:235]
	v_add_u32_e32 v194, 0x40000, v146
	v_lshrrev_b32_e32 v198, 1, v194
	v_add_u32_e32 v144, 0x100000, v146
	global_load_dwordx4 v[220:223], v144, s[52:53] offset:0
	global_load_dwordx4 v[224:227], v144, s[52:53] offset:16
	global_load_dwordx4 v[228:231], v144, s[52:53] offset:512
	global_load_dwordx4 v[232:235], v144, s[52:53] offset:528
	global_store_dwordx4 v194, v[92:95], s[14:15] offset:0
	global_store_dwordx4 v194, v[88:91], s[14:15] offset:16
	global_store_dwordx4 v194, v[84:87], s[14:15] offset:512
	global_store_dwordx4 v194, v[80:83], s[14:15] offset:528
	v_pk_mul_f32 v[204:205], v[92:93], v[174:175]
	v_pk_mul_f32 v[206:207], v[94:95], v[176:177]
	v_cvt_pk_bf16_f32 v200, v204, v205
	v_cvt_pk_bf16_f32 v201, v206, v207
	v_pk_mul_f32 v[204:205], v[88:89], v[178:179]
	v_pk_mul_f32 v[206:207], v[90:91], v[180:181]
	v_cvt_pk_bf16_f32 v202, v204, v205
	v_cvt_pk_bf16_f32 v203, v206, v207
	global_store_dwordx4 v198, v[200:203], s[20:21]
	v_pk_mul_f32 v[204:205], v[84:85], v[182:183]
	v_pk_mul_f32 v[206:207], v[86:87], v[184:185]
	v_cvt_pk_bf16_f32 v208, v204, v205
	v_cvt_pk_bf16_f32 v209, v206, v207
	v_pk_mul_f32 v[204:205], v[80:81], v[186:187]
	v_pk_mul_f32 v[206:207], v[82:83], v[188:189]
	v_cvt_pk_bf16_f32 v210, v204, v205
	v_cvt_pk_bf16_f32 v211, v206, v207
	global_store_dwordx4 v198, v[208:211], s[20:21] offset:256
	v_mul_f32_e32 v190, v93, v93
	v_mul_f32_e32 v195, v95, v95
	v_fmac_f32_e32 v190, v92, v92
	v_fmac_f32_e32 v195, v94, v94
	v_add_f32_e32 v190, v190, v195
	v_mul_f32_e32 v191, v89, v89
	v_mul_f32_e32 v195, v91, v91
	v_fmac_f32_e32 v191, v88, v88
	v_fmac_f32_e32 v195, v90, v90
	v_add_f32_e32 v191, v191, v195
	v_mul_f32_e32 v192, v85, v85
	v_mul_f32_e32 v195, v87, v87
	v_fmac_f32_e32 v192, v84, v84
	v_fmac_f32_e32 v195, v86, v86
	v_add_f32_e32 v192, v192, v195
	v_mul_f32_e32 v193, v81, v81
	v_mul_f32_e32 v195, v83, v83
	v_fmac_f32_e32 v193, v80, v80
	v_fmac_f32_e32 v195, v82, v82
	v_add_f32_e32 v193, v193, v195
	v_add_f32_e32 v190, v190, v191
	v_add_f32_e32 v190, v190, v192
	v_add_f32_e32 v190, v190, v193
	ds_bpermute_b32 v195, v196, v190
	s_waitcnt lgkmcnt(0)
	v_add_f32_e32 v190, v190, v195
	ds_bpermute_b32 v195, v197, v190
	s_waitcnt lgkmcnt(0)
	v_add_f32_e32 v214, v190, v195
	s_waitcnt vmcnt(16)
	v_pk_fma_f32 v[76:77], v[76:77], v[158:159], v[236:237]
	v_pk_fma_f32 v[78:79], v[78:79], v[160:161], v[238:239]
	v_pk_fma_f32 v[72:73], v[72:73], v[162:163], v[240:241]
	v_pk_fma_f32 v[74:75], v[74:75], v[164:165], v[242:243]
	v_pk_fma_f32 v[68:69], v[68:69], v[166:167], v[244:245]
	v_pk_fma_f32 v[70:71], v[70:71], v[168:169], v[246:247]
	v_pk_fma_f32 v[64:65], v[64:65], v[170:171], v[248:249]
	v_pk_fma_f32 v[66:67], v[66:67], v[172:173], v[250:251]
	v_add_u32_e32 v194, 0x60000, v146
	v_lshrrev_b32_e32 v198, 1, v194
	v_add_u32_e32 v144, 0x120000, v146
	global_load_dwordx4 v[236:239], v144, s[52:53] offset:0
	global_load_dwordx4 v[240:243], v144, s[52:53] offset:16
	global_load_dwordx4 v[244:247], v144, s[52:53] offset:512
	global_load_dwordx4 v[248:251], v144, s[52:53] offset:528
	global_store_dwordx4 v194, v[76:79], s[14:15] offset:0
	global_store_dwordx4 v194, v[72:75], s[14:15] offset:16
	global_store_dwordx4 v194, v[68:71], s[14:15] offset:512
	global_store_dwordx4 v194, v[64:67], s[14:15] offset:528
	v_pk_mul_f32 v[204:205], v[76:77], v[174:175]
	v_pk_mul_f32 v[206:207], v[78:79], v[176:177]
	v_cvt_pk_bf16_f32 v200, v204, v205
	v_cvt_pk_bf16_f32 v201, v206, v207
	v_pk_mul_f32 v[204:205], v[72:73], v[178:179]
	v_pk_mul_f32 v[206:207], v[74:75], v[180:181]
	v_cvt_pk_bf16_f32 v202, v204, v205
	v_cvt_pk_bf16_f32 v203, v206, v207
	global_store_dwordx4 v198, v[200:203], s[20:21]
	v_pk_mul_f32 v[204:205], v[68:69], v[182:183]
	v_pk_mul_f32 v[206:207], v[70:71], v[184:185]
	v_cvt_pk_bf16_f32 v208, v204, v205
	v_cvt_pk_bf16_f32 v209, v206, v207
	v_pk_mul_f32 v[204:205], v[64:65], v[186:187]
	v_pk_mul_f32 v[206:207], v[66:67], v[188:189]
	v_cvt_pk_bf16_f32 v210, v204, v205
	v_cvt_pk_bf16_f32 v211, v206, v207
	global_store_dwordx4 v198, v[208:211], s[20:21] offset:256
	v_mul_f32_e32 v190, v77, v77
	v_mul_f32_e32 v195, v79, v79
	v_fmac_f32_e32 v190, v76, v76
	v_fmac_f32_e32 v195, v78, v78
	v_add_f32_e32 v190, v190, v195
	v_mul_f32_e32 v191, v73, v73
	v_mul_f32_e32 v195, v75, v75
	v_fmac_f32_e32 v191, v72, v72
	v_fmac_f32_e32 v195, v74, v74
	v_add_f32_e32 v191, v191, v195
	v_mul_f32_e32 v192, v69, v69
	v_mul_f32_e32 v195, v71, v71
	v_fmac_f32_e32 v192, v68, v68
	v_fmac_f32_e32 v195, v70, v70
	v_add_f32_e32 v192, v192, v195
	v_mul_f32_e32 v193, v65, v65
	v_mul_f32_e32 v195, v67, v67
	v_fmac_f32_e32 v193, v64, v64
	v_fmac_f32_e32 v195, v66, v66
	v_add_f32_e32 v193, v193, v195
	v_add_f32_e32 v190, v190, v191
	v_add_f32_e32 v190, v190, v192
	v_add_f32_e32 v190, v190, v193
	ds_bpermute_b32 v195, v196, v190
	s_waitcnt lgkmcnt(0)
	v_add_f32_e32 v190, v190, v195
	ds_bpermute_b32 v195, v197, v190
	s_waitcnt lgkmcnt(0)
	v_add_f32_e32 v215, v190, v195
	s_waitcnt vmcnt(16)
	v_pk_fma_f32 v[60:61], v[60:61], v[158:159], v[220:221]
	v_pk_fma_f32 v[62:63], v[62:63], v[160:161], v[222:223]
	v_pk_fma_f32 v[56:57], v[56:57], v[162:163], v[224:225]
	v_pk_fma_f32 v[58:59], v[58:59], v[164:165], v[226:227]
	v_pk_fma_f32 v[52:53], v[52:53], v[166:167], v[228:229]
	v_pk_fma_f32 v[54:55], v[54:55], v[168:169], v[230:231]
	v_pk_fma_f32 v[48:49], v[48:49], v[170:171], v[232:233]
	v_pk_fma_f32 v[50:51], v[50:51], v[172:173], v[234:235]
	v_add_u32_e32 v194, 0x100000, v146
	v_lshrrev_b32_e32 v198, 1, v194
	v_add_u32_e32 v144, 0x140000, v146
	global_load_dwordx4 v[220:223], v144, s[52:53] offset:0
	global_load_dwordx4 v[224:227], v144, s[52:53] offset:16
	global_load_dwordx4 v[228:231], v144, s[52:53] offset:512
	global_load_dwordx4 v[232:235], v144, s[52:53] offset:528
	global_store_dwordx4 v194, v[60:63], s[14:15] offset:0
	global_store_dwordx4 v194, v[56:59], s[14:15] offset:16
	global_store_dwordx4 v194, v[52:55], s[14:15] offset:512
	global_store_dwordx4 v194, v[48:51], s[14:15] offset:528
	v_pk_mul_f32 v[204:205], v[60:61], v[174:175]
	v_pk_mul_f32 v[206:207], v[62:63], v[176:177]
	v_cvt_pk_bf16_f32 v200, v204, v205
	v_cvt_pk_bf16_f32 v201, v206, v207
	v_pk_mul_f32 v[204:205], v[56:57], v[178:179]
	v_pk_mul_f32 v[206:207], v[58:59], v[180:181]
	v_cvt_pk_bf16_f32 v202, v204, v205
	v_cvt_pk_bf16_f32 v203, v206, v207
	global_store_dwordx4 v198, v[200:203], s[20:21]
	v_pk_mul_f32 v[204:205], v[52:53], v[182:183]
	v_pk_mul_f32 v[206:207], v[54:55], v[184:185]
	v_cvt_pk_bf16_f32 v208, v204, v205
	v_cvt_pk_bf16_f32 v209, v206, v207
	v_pk_mul_f32 v[204:205], v[48:49], v[186:187]
	v_pk_mul_f32 v[206:207], v[50:51], v[188:189]
	v_cvt_pk_bf16_f32 v210, v204, v205
	v_cvt_pk_bf16_f32 v211, v206, v207
	global_store_dwordx4 v198, v[208:211], s[20:21] offset:256
	v_mul_f32_e32 v190, v61, v61
	v_mul_f32_e32 v195, v63, v63
	v_fmac_f32_e32 v190, v60, v60
	v_fmac_f32_e32 v195, v62, v62
	v_add_f32_e32 v190, v190, v195
	v_mul_f32_e32 v191, v57, v57
	v_mul_f32_e32 v195, v59, v59
	v_fmac_f32_e32 v191, v56, v56
	v_fmac_f32_e32 v195, v58, v58
	v_add_f32_e32 v191, v191, v195
	v_mul_f32_e32 v192, v53, v53
	v_mul_f32_e32 v195, v55, v55
	v_fmac_f32_e32 v192, v52, v52
	v_fmac_f32_e32 v195, v54, v54
	v_add_f32_e32 v192, v192, v195
	v_mul_f32_e32 v193, v49, v49
	v_mul_f32_e32 v195, v51, v51
	v_fmac_f32_e32 v193, v48, v48
	v_fmac_f32_e32 v195, v50, v50
	v_add_f32_e32 v193, v193, v195
	v_add_f32_e32 v190, v190, v191
	v_add_f32_e32 v190, v190, v192
	v_add_f32_e32 v190, v190, v193
	ds_bpermute_b32 v195, v196, v190
	s_waitcnt lgkmcnt(0)
	v_add_f32_e32 v190, v190, v195
	ds_bpermute_b32 v195, v197, v190
	s_waitcnt lgkmcnt(0)
	v_add_f32_e32 v216, v190, v195
	s_waitcnt vmcnt(16)
	v_pk_fma_f32 v[44:45], v[44:45], v[158:159], v[236:237]
	v_pk_fma_f32 v[46:47], v[46:47], v[160:161], v[238:239]
	v_pk_fma_f32 v[40:41], v[40:41], v[162:163], v[240:241]
	v_pk_fma_f32 v[42:43], v[42:43], v[164:165], v[242:243]
	v_pk_fma_f32 v[36:37], v[36:37], v[166:167], v[244:245]
	v_pk_fma_f32 v[38:39], v[38:39], v[168:169], v[246:247]
	v_pk_fma_f32 v[32:33], v[32:33], v[170:171], v[248:249]
	v_pk_fma_f32 v[34:35], v[34:35], v[172:173], v[250:251]
	v_add_u32_e32 v194, 0x120000, v146
	v_lshrrev_b32_e32 v198, 1, v194
	v_add_u32_e32 v144, 0x160000, v146
	global_load_dwordx4 v[236:239], v144, s[52:53] offset:0
	global_load_dwordx4 v[240:243], v144, s[52:53] offset:16
	global_load_dwordx4 v[244:247], v144, s[52:53] offset:512
	global_load_dwordx4 v[248:251], v144, s[52:53] offset:528
	global_store_dwordx4 v194, v[44:47], s[14:15] offset:0
	global_store_dwordx4 v194, v[40:43], s[14:15] offset:16
	global_store_dwordx4 v194, v[36:39], s[14:15] offset:512
	global_store_dwordx4 v194, v[32:35], s[14:15] offset:528
	v_pk_mul_f32 v[204:205], v[44:45], v[174:175]
	v_pk_mul_f32 v[206:207], v[46:47], v[176:177]
	v_cvt_pk_bf16_f32 v200, v204, v205
	v_cvt_pk_bf16_f32 v201, v206, v207
	v_pk_mul_f32 v[204:205], v[40:41], v[178:179]
	v_pk_mul_f32 v[206:207], v[42:43], v[180:181]
	v_cvt_pk_bf16_f32 v202, v204, v205
	v_cvt_pk_bf16_f32 v203, v206, v207
	global_store_dwordx4 v198, v[200:203], s[20:21]
	v_pk_mul_f32 v[204:205], v[36:37], v[182:183]
	v_pk_mul_f32 v[206:207], v[38:39], v[184:185]
	v_cvt_pk_bf16_f32 v208, v204, v205
	v_cvt_pk_bf16_f32 v209, v206, v207
	v_pk_mul_f32 v[204:205], v[32:33], v[186:187]
	v_pk_mul_f32 v[206:207], v[34:35], v[188:189]
	v_cvt_pk_bf16_f32 v210, v204, v205
	v_cvt_pk_bf16_f32 v211, v206, v207
	global_store_dwordx4 v198, v[208:211], s[20:21] offset:256
	v_mul_f32_e32 v190, v45, v45
	v_mul_f32_e32 v195, v47, v47
	v_fmac_f32_e32 v190, v44, v44
	v_fmac_f32_e32 v195, v46, v46
	v_add_f32_e32 v190, v190, v195
	v_mul_f32_e32 v191, v41, v41
	v_mul_f32_e32 v195, v43, v43
	v_fmac_f32_e32 v191, v40, v40
	v_fmac_f32_e32 v195, v42, v42
	v_add_f32_e32 v191, v191, v195
	v_mul_f32_e32 v192, v37, v37
	v_mul_f32_e32 v195, v39, v39
	v_fmac_f32_e32 v192, v36, v36
	v_fmac_f32_e32 v195, v38, v38
	v_add_f32_e32 v192, v192, v195
	v_mul_f32_e32 v193, v33, v33
	v_mul_f32_e32 v195, v35, v35
	v_fmac_f32_e32 v193, v32, v32
	v_fmac_f32_e32 v195, v34, v34
	v_add_f32_e32 v193, v193, v195
	v_add_f32_e32 v190, v190, v191
	v_add_f32_e32 v190, v190, v192
	v_add_f32_e32 v190, v190, v193
	ds_bpermute_b32 v195, v196, v190
	s_waitcnt lgkmcnt(0)
	v_add_f32_e32 v190, v190, v195
	ds_bpermute_b32 v195, v197, v190
	s_waitcnt lgkmcnt(0)
	v_add_f32_e32 v217, v190, v195
	s_waitcnt vmcnt(16)
	v_pk_fma_f32 v[28:29], v[28:29], v[158:159], v[220:221]
	v_pk_fma_f32 v[30:31], v[30:31], v[160:161], v[222:223]
	v_pk_fma_f32 v[24:25], v[24:25], v[162:163], v[224:225]
	v_pk_fma_f32 v[26:27], v[26:27], v[164:165], v[226:227]
	v_pk_fma_f32 v[20:21], v[20:21], v[166:167], v[228:229]
	v_pk_fma_f32 v[22:23], v[22:23], v[168:169], v[230:231]
	v_pk_fma_f32 v[16:17], v[16:17], v[170:171], v[232:233]
	v_pk_fma_f32 v[18:19], v[18:19], v[172:173], v[234:235]
	v_add_u32_e32 v194, 0x140000, v146
	v_lshrrev_b32_e32 v198, 1, v194
	global_store_dwordx4 v194, v[28:31], s[14:15] offset:0
	global_store_dwordx4 v194, v[24:27], s[14:15] offset:16
	global_store_dwordx4 v194, v[20:23], s[14:15] offset:512
	global_store_dwordx4 v194, v[16:19], s[14:15] offset:528
	v_pk_mul_f32 v[204:205], v[28:29], v[174:175]
	v_pk_mul_f32 v[206:207], v[30:31], v[176:177]
	v_cvt_pk_bf16_f32 v200, v204, v205
	v_cvt_pk_bf16_f32 v201, v206, v207
	v_pk_mul_f32 v[204:205], v[24:25], v[178:179]
	v_pk_mul_f32 v[206:207], v[26:27], v[180:181]
	v_cvt_pk_bf16_f32 v202, v204, v205
	v_cvt_pk_bf16_f32 v203, v206, v207
	global_store_dwordx4 v198, v[200:203], s[20:21]
	v_pk_mul_f32 v[204:205], v[20:21], v[182:183]
	v_pk_mul_f32 v[206:207], v[22:23], v[184:185]
	v_cvt_pk_bf16_f32 v208, v204, v205
	v_cvt_pk_bf16_f32 v209, v206, v207
	v_pk_mul_f32 v[204:205], v[16:17], v[186:187]
	v_pk_mul_f32 v[206:207], v[18:19], v[188:189]
	v_cvt_pk_bf16_f32 v210, v204, v205
	v_cvt_pk_bf16_f32 v211, v206, v207
	global_store_dwordx4 v198, v[208:211], s[20:21] offset:256
	v_mul_f32_e32 v190, v29, v29
	v_mul_f32_e32 v195, v31, v31
	v_fmac_f32_e32 v190, v28, v28
	v_fmac_f32_e32 v195, v30, v30
	v_add_f32_e32 v190, v190, v195
	v_mul_f32_e32 v191, v25, v25
	v_mul_f32_e32 v195, v27, v27
	v_fmac_f32_e32 v191, v24, v24
	v_fmac_f32_e32 v195, v26, v26
	v_add_f32_e32 v191, v191, v195
	v_mul_f32_e32 v192, v21, v21
	v_mul_f32_e32 v195, v23, v23
	v_fmac_f32_e32 v192, v20, v20
	v_fmac_f32_e32 v195, v22, v22
	v_add_f32_e32 v192, v192, v195
	v_mul_f32_e32 v193, v17, v17
	v_mul_f32_e32 v195, v19, v19
	v_fmac_f32_e32 v193, v16, v16
	v_fmac_f32_e32 v195, v18, v18
	v_add_f32_e32 v193, v193, v195
	v_add_f32_e32 v190, v190, v191
	v_add_f32_e32 v190, v190, v192
	v_add_f32_e32 v190, v190, v193
	ds_bpermute_b32 v195, v196, v190
	s_waitcnt lgkmcnt(0)
	v_add_f32_e32 v190, v190, v195
	ds_bpermute_b32 v195, v197, v190
	s_waitcnt lgkmcnt(0)
	v_add_f32_e32 v218, v190, v195
	s_waitcnt vmcnt(12)
	v_pk_fma_f32 v[12:13], v[12:13], v[158:159], v[236:237]
	v_pk_fma_f32 v[14:15], v[14:15], v[160:161], v[238:239]
	v_pk_fma_f32 v[8:9], v[8:9], v[162:163], v[240:241]
	v_pk_fma_f32 v[10:11], v[10:11], v[164:165], v[242:243]
	v_pk_fma_f32 v[4:5], v[4:5], v[166:167], v[244:245]
	v_pk_fma_f32 v[6:7], v[6:7], v[168:169], v[246:247]
	v_pk_fma_f32 v[0:1], v[0:1], v[170:171], v[248:249]
	v_pk_fma_f32 v[2:3], v[2:3], v[172:173], v[250:251]
	v_add_u32_e32 v194, 0x160000, v146
	v_lshrrev_b32_e32 v198, 1, v194
	global_store_dwordx4 v194, v[12:15], s[14:15] offset:0
	global_store_dwordx4 v194, v[8:11], s[14:15] offset:16
	global_store_dwordx4 v194, v[4:7], s[14:15] offset:512
	global_store_dwordx4 v194, v[0:3], s[14:15] offset:528
	v_pk_mul_f32 v[204:205], v[12:13], v[174:175]
	v_pk_mul_f32 v[206:207], v[14:15], v[176:177]
	v_cvt_pk_bf16_f32 v200, v204, v205
	v_cvt_pk_bf16_f32 v201, v206, v207
	v_pk_mul_f32 v[204:205], v[8:9], v[178:179]
	v_pk_mul_f32 v[206:207], v[10:11], v[180:181]
	v_cvt_pk_bf16_f32 v202, v204, v205
	v_cvt_pk_bf16_f32 v203, v206, v207
	global_store_dwordx4 v198, v[200:203], s[20:21]
	v_pk_mul_f32 v[204:205], v[4:5], v[182:183]
	v_pk_mul_f32 v[206:207], v[6:7], v[184:185]
	v_cvt_pk_bf16_f32 v208, v204, v205
	v_cvt_pk_bf16_f32 v209, v206, v207
	v_pk_mul_f32 v[204:205], v[0:1], v[186:187]
	v_pk_mul_f32 v[206:207], v[2:3], v[188:189]
	v_cvt_pk_bf16_f32 v210, v204, v205
	v_cvt_pk_bf16_f32 v211, v206, v207
	global_store_dwordx4 v198, v[208:211], s[20:21] offset:256
	v_mul_f32_e32 v190, v13, v13
	v_mul_f32_e32 v195, v15, v15
	v_fmac_f32_e32 v190, v12, v12
	v_fmac_f32_e32 v195, v14, v14
	v_add_f32_e32 v190, v190, v195
	v_mul_f32_e32 v191, v9, v9
	v_mul_f32_e32 v195, v11, v11
	v_fmac_f32_e32 v191, v8, v8
	v_fmac_f32_e32 v195, v10, v10
	v_add_f32_e32 v191, v191, v195
	v_mul_f32_e32 v192, v5, v5
	v_mul_f32_e32 v195, v7, v7
	v_fmac_f32_e32 v192, v4, v4
	v_fmac_f32_e32 v195, v6, v6
	v_add_f32_e32 v192, v192, v195
	v_mul_f32_e32 v193, v1, v1
	v_mul_f32_e32 v195, v3, v3
	v_fmac_f32_e32 v193, v0, v0
	v_fmac_f32_e32 v195, v2, v2
	v_add_f32_e32 v193, v193, v195
	v_add_f32_e32 v190, v190, v191
	v_add_f32_e32 v190, v190, v192
	v_add_f32_e32 v190, v190, v193
	ds_bpermute_b32 v195, v196, v190
	s_waitcnt lgkmcnt(0)
	v_add_f32_e32 v190, v190, v195
	ds_bpermute_b32 v195, v197, v190
	s_waitcnt lgkmcnt(0)
	v_add_f32_e32 v219, v190, v195
	s_and_saveexec_b64 s[30:31], s[0:1]
	global_atomic_add_f32 v147, v212, s[18:19]
	global_atomic_add_f32 v147, v213, s[18:19] offset:64
	global_atomic_add_f32 v147, v214, s[18:19] offset:128
	global_atomic_add_f32 v147, v215, s[18:19] offset:192
	global_atomic_add_f32 v147, v216, s[18:19] offset:512
	global_atomic_add_f32 v147, v217, s[18:19] offset:576
	global_atomic_add_f32 v147, v218, s[18:19] offset:640
	global_atomic_add_f32 v147, v219, s[18:19] offset:704
	s_or_b64 exec, exec, s[30:31]
	s_branch .Lp5_epi_tail
	v_lshl_add_u32 v146, s30, 8, v150
	s_ashr_i32 s13, s30, 3
	s_mul_hi_i32 s23, s13, 0xc000
	s_mul_i32 s13, s13, 0xc000
	v_lshl_or_b32 v148, s28, 8, v152
	v_ashrrev_i32_e32 v147, 31, v146
	s_add_u32 s13, s64, s13
	v_lshlrev_b64 v[182:183], 11, v[146:147]
	v_ashrrev_i32_e32 v149, 31, v148
	v_readlane_b32 s68, v253, 24
	s_addc_u32 s23, s65, s23
	v_lshl_add_u64 v[184:185], v[182:183], 0, v[148:149]
	v_readlane_b32 s69, v253, 25
	s_add_u32 s30, s13, 0x4000
	v_lshlrev_b64 v[166:167], 2, v[184:185]
	s_mov_b64 s[52:53], s[68:69]
	s_addc_u32 s31, s23, 0
	v_lshlrev_b64 v[174:175], 2, v[148:149]
	v_lshl_add_u64 v[186:187], s[52:53], 0, v[166:167]
	v_lshl_add_u64 v[144:145], s[30:31], 0, v[174:175]
	global_load_dwordx4 v[158:161], v[186:187], off
	global_load_dwordx4 v[162:165], v[144:145], off
	v_lshl_add_u64 v[170:171], s[14:15], 0, v[166:167]
	s_add_u32 s28, s13, 0x8000
	v_readlane_b32 s82, v253, 38
	v_readlane_b32 s83, v253, 39
	s_addc_u32 s29, s23, 0
	s_mov_b64 s[66:67], s[82:83]
	v_lshl_add_u64 v[184:185], v[184:185], 1, s[20:21]
	v_readlane_b32 s70, v253, 26
	v_readlane_b32 s71, v253, 27
	v_readlane_b32 s72, v253, 28
	v_readlane_b32 s73, v253, 29
	v_readlane_b32 s74, v253, 30
	v_readlane_b32 s75, v253, 31
	v_readlane_b32 s76, v253, 32
	v_readlane_b32 s77, v253, 33
	v_readlane_b32 s78, v253, 34
	v_readlane_b32 s79, v253, 35
	v_readlane_b32 s80, v253, 36
	v_readlane_b32 s81, v253, 37
	s_waitcnt vmcnt(0)
	v_pk_fma_f32 v[160:161], v[126:127], v[164:165], v[160:161]
	v_pk_fma_f32 v[158:159], v[124:125], v[162:163], v[158:159]
	global_store_dwordx4 v[170:171], v[158:161], off
	global_load_dwordx4 v[162:165], v[144:145], off offset:16
	global_load_dwordx4 v[166:169], v[186:187], off offset:16
	v_lshl_add_u64 v[126:127], s[28:29], 0, v[174:175]
	v_or_b32_e32 v124, 0x80, v148
	v_ashrrev_i32_e32 v125, 31, v124
	v_lshlrev_b64 v[188:189], 2, v[124:125]
	v_lshl_add_u64 v[190:191], v[182:183], 0, v[124:125]
	s_waitcnt vmcnt(0)
	v_pk_fma_f32 v[164:165], v[122:123], v[164:165], v[168:169]
	v_pk_fma_f32 v[162:163], v[120:121], v[162:163], v[166:167]
	global_store_dwordx4 v[170:171], v[162:165], off offset:16
	global_load_dwordx4 v[166:169], v[126:127], off
	s_nop 0
	global_load_dwordx4 v[170:173], v[126:127], off offset:16
	v_lshl_add_u64 v[120:121], s[66:67], 0, v[174:175]
	global_load_dwordx4 v[174:177], v[120:121], off
	global_load_dwordx4 v[178:181], v[120:121], off offset:16
	v_lshl_add_u64 v[122:123], s[30:31], 0, v[188:189]
	s_waitcnt vmcnt(3)
	v_pk_add_f32 v[168:169], v[168:169], 1.0 op_sel_hi:[1,0]
	v_pk_add_f32 v[166:167], v[166:167], 1.0 op_sel_hi:[1,0]
	s_waitcnt vmcnt(2)
	v_pk_add_f32 v[172:173], v[172:173], 1.0 op_sel_hi:[1,0]
	v_pk_add_f32 v[170:171], v[170:171], 1.0 op_sel_hi:[1,0]
	s_waitcnt vmcnt(1)
	v_pk_mul_f32 v[168:169], v[176:177], v[168:169]
	v_pk_mul_f32 v[166:167], v[174:175], v[166:167]
	s_waitcnt vmcnt(0)
	v_pk_mul_f32 v[172:173], v[180:181], v[172:173]
	v_pk_mul_f32 v[170:171], v[178:179], v[170:171]
	v_pk_mul_f32 v[168:169], v[160:161], v[168:169]
	v_pk_mul_f32 v[166:167], v[158:159], v[166:167]
	v_pk_mul_f32 v[172:173], v[164:165], v[172:173]
	v_pk_mul_f32 v[170:171], v[162:163], v[170:171]
	v_cvt_pk_bf16_f32 v166, v166, v167
	v_cvt_pk_bf16_f32 v167, v168, v169
	v_cvt_pk_bf16_f32 v168, v170, v171
	v_cvt_pk_bf16_f32 v169, v172, v173
	global_store_dwordx4 v[184:185], v[166:169], off
	global_load_dwordx4 v[166:169], v[122:123], off
	s_nop 0
	global_load_dwordx4 v[170:173], v[186:187], off offset:512
	v_lshl_add_u64 v[178:179], v[190:191], 2, s[14:15]
	s_waitcnt vmcnt(0)
	v_pk_fma_f32 v[168:169], v[118:119], v[168:169], v[172:173]
	v_pk_fma_f32 v[166:167], v[116:117], v[166:167], v[170:171]
	global_store_dwordx4 v[178:179], v[166:169], off
	global_load_dwordx4 v[170:173], v[122:123], off offset:16
	global_load_dwordx4 v[174:177], v[186:187], off offset:528
	v_lshl_add_u64 v[116:117], s[28:29], 0, v[188:189]
	v_mul_f32_e32 v118, v165, v165
	v_fmac_f32_e32 v118, v164, v164
	s_waitcnt vmcnt(0)
	v_pk_fma_f32 v[172:173], v[114:115], v[172:173], v[176:177]
	v_pk_fma_f32 v[170:171], v[112:113], v[170:171], v[174:175]
	global_store_dwordx4 v[178:179], v[170:173], off offset:16
	global_load_dwordx4 v[174:177], v[116:117], off
	s_nop 0
	global_load_dwordx4 v[178:181], v[116:117], off offset:16
	global_load_dwordx4 v[182:185], v[120:121], off offset:512
	global_load_dwordx4 v[186:189], v[120:121], off offset:528
	v_and_b32_e32 v113, 64, v156
	v_xor_b32_e32 v112, 16, v156
	v_add_u32_e32 v113, 64, v113
	v_cmp_lt_i32_e32 vcc, v112, v113
	v_mul_f32_e32 v115, v161, v161
	v_fmac_f32_e32 v115, v160, v160
	v_cndmask_b32_e32 v112, v156, v112, vcc
	v_lshlrev_b32_e32 v114, 2, v112
	v_mul_f32_e32 v112, v159, v159
	v_fmac_f32_e32 v112, v158, v158
	v_add_f32_e32 v112, v112, v115
	v_mul_f32_e32 v115, v163, v163
	v_fmac_f32_e32 v115, v162, v162
	v_add_f32_e32 v115, v115, v118
	v_add_f32_e32 v112, v112, v115
	v_mul_f32_e32 v115, v167, v167
	v_mul_f32_e32 v118, v169, v169
	v_fmac_f32_e32 v115, v166, v166
	v_fmac_f32_e32 v118, v168, v168
	v_add_f32_e32 v115, v115, v118
	v_add_f32_e32 v112, v112, v115
	v_mul_f32_e32 v115, v171, v171
	v_mul_f32_e32 v118, v173, v173
	v_fmac_f32_e32 v115, v170, v170
	v_fmac_f32_e32 v118, v172, v172
	v_add_f32_e32 v115, v115, v118
	v_add_f32_e32 v112, v112, v115
	ds_bpermute_b32 v118, v114, v112
	v_xor_b32_e32 v115, 32, v156
	v_cmp_lt_i32_e32 vcc, v115, v113
	s_waitcnt lgkmcnt(0)
	v_add_f32_e32 v112, v112, v118
	v_cndmask_b32_e32 v113, v156, v115, vcc
	v_lshlrev_b32_e32 v115, 2, v113
	ds_bpermute_b32 v113, v115, v112
	s_waitcnt vmcnt(3)
	v_pk_add_f32 v[118:119], v[176:177], 1.0 op_sel_hi:[1,0]
	v_pk_add_f32 v[158:159], v[174:175], 1.0 op_sel_hi:[1,0]
	s_waitcnt vmcnt(2)
	v_pk_add_f32 v[160:161], v[180:181], 1.0 op_sel_hi:[1,0]
	v_pk_add_f32 v[162:163], v[178:179], 1.0 op_sel_hi:[1,0]
	s_waitcnt vmcnt(1)
	v_pk_mul_f32 v[118:119], v[184:185], v[118:119]
	v_pk_mul_f32 v[158:159], v[182:183], v[158:159]
	s_waitcnt vmcnt(0)
	v_pk_mul_f32 v[160:161], v[188:189], v[160:161]
	v_pk_mul_f32 v[162:163], v[186:187], v[162:163]
	v_pk_mul_f32 v[118:119], v[168:169], v[118:119]
	v_pk_mul_f32 v[158:159], v[166:167], v[158:159]
	v_pk_mul_f32 v[164:165], v[172:173], v[160:161]
	v_pk_mul_f32 v[160:161], v[170:171], v[162:163]
	v_cvt_pk_bf16_f32 v158, v158, v159
	v_cvt_pk_bf16_f32 v159, v118, v119
	v_cvt_pk_bf16_f32 v160, v160, v161
	v_cvt_pk_bf16_f32 v161, v164, v165
	v_lshl_add_u64 v[118:119], v[190:191], 1, s[20:21]
	global_store_dwordx4 v[118:119], v[158:161], off
	s_and_saveexec_b64 s[28:29], s[0:1]
	s_cbranch_execz .LBB0_766
	v_lshl_add_u64 v[118:119], v[146:147], 2, s[18:19]
	s_waitcnt lgkmcnt(0)
	v_add_f32_e32 v112, v112, v113
	global_atomic_add_f32 v[118:119], v112, off

.Lp5_epi_tail:
	s_andn2_b64 vcc, exec, s[40:41]
	s_mov_b64 s[28:29], -1
	s_cbranch_vccnz .LBB0_753
	s_andn2_b64 vcc, exec, s[4:5]
	s_cbranch_vccnz .LBB0_752
	s_barrier
	s_branch .LBB0_752
